# fast row path for all non-edge rows; pooled-branch scale vectors hoisted out of the pool GEMM epilogue ladder
# baseline (speedup 1.0000x reference)
.LBB0_276:
	s_or_b64 exec, exec, s[0:1]
	v_readlane_b32 s4, v250, 5
	v_mov_b32_e32 v6, v171
	s_mov_b64 s[80:81], 0
	v_readlane_b32 s8, v250, 9
	s_waitcnt lgkmcnt(0)
	s_barrier
	v_readlane_b32 s9, v250, 10
	s_add_u32 s14, s8, s80
	v_ashrrev_i32_e32 v8, 6, v6
	v_readlane_b32 s0, v250, 33
	s_addc_u32 s15, s9, s81
	v_readlane_b32 s6, v250, 7
	v_add_u32_e32 v16, s0, v8
	s_add_u32 s0, s14, 0x6300000
	s_addc_u32 s1, s15, 0
	s_movk_i32 s4, 0x2010
	v_readlane_b32 s5, v250, 6
	v_readlane_b32 s7, v250, 8
	v_readlane_b32 s10, v250, 11
	v_readlane_b32 s11, v250, 12
	v_cmp_gt_i32_e32 vcc, s4, v16
	s_mov_b64 s[4:5], exec
	v_writelane_b32 v250, s4, 36
	s_and_b64 s[36:37], s[4:5], vcc
	s_movk_i32 s6, 0xff
	v_writelane_b32 v250, s5, 37
	s_mov_b64 exec, s[36:37]
	s_cbranch_execz .LBB0_339
	v_readlane_b32 s38, v250, 30
	s_mov_b64 s[40:41], s[14:15]
	v_readlane_b32 s4, v252, 3
	v_readlane_b32 s39, v250, 31
	v_readlane_b32 s5, v252, 4
	v_readlane_b32 s4, v250, 33
	v_ashrrev_i32_e32 v17, 31, v16
	s_lshl_b64 s[36:37], s[38:39], 8
	v_readlane_b32 s14, v252, 13
	v_and_b32_e32 v9, 63, v6
	v_add3_u32 v8, v8, s4, -15
	v_lshlrev_b64 v[12:13], 14, v[16:17]
	v_readlane_b32 s4, v251, 62
	v_readlane_b32 s15, v252, 14
	s_add_u32 s36, s14, s36
	v_lshl_or_b32 v10, v9, 1, v12
	v_mov_b32_e32 v11, v13
	v_readlane_b32 s5, v251, 63
	v_readlane_b32 s12, v252, 11
	s_addc_u32 s37, s15, s37
	s_lshl_b64 s[38:39], s[38:39], 10
	v_lshl_add_u64 v[10:11], s[4:5], 0, v[10:11]
	v_readlane_b32 s4, v250, 27
	v_readlane_b32 s6, v252, 5
	v_readlane_b32 s7, v252, 6
	v_readlane_b32 s8, v252, 7
	v_readlane_b32 s9, v252, 8
	v_readlane_b32 s10, v252, 9
	v_readlane_b32 s11, v252, 10
	v_readlane_b32 s13, v252, 12
	s_add_u32 s38, s12, s38
	v_readlane_b32 s5, v250, 28
	s_addc_u32 s39, s13, s39
	s_mov_b32 s12, s4
	s_ashr_i32 s13, s4, 31
	v_readlane_b32 s4, v250, 5
	v_readlane_b32 s5, v250, 6
	v_lshlrev_b32_e32 v168, 2, v9
	v_lshlrev_b32_e32 v0, 4, v9
	v_bfe_u32 v59, v6, 4, 2
	v_lshlrev_b32_e32 v4, 2, v6
	v_and_b32_e32 v6, 7, v6
	v_lshlrev_b32_e32 v9, 3, v9
	v_lshlrev_b64 v[14:15], 9, v[16:17]
	v_lshlrev_b64 v[16:17], 11, v[16:17]
	v_readlane_b32 s4, v250, 0
	s_mov_b64 s[14:15], s[40:41]
	v_lshlrev_b32_e32 v6, 1, v6
	v_mov_b32_e32 v7, v169
	v_or_b32_e32 v16, v16, v9
	v_readlane_b32 s5, v250, 1
	v_mov_b32_e32 v1, v169
	v_lshl_add_u64 v[2:3], s[36:37], 0, v[168:169]
	v_lshl_add_u64 v[6:7], s[14:15], 0, v[6:7]
	s_mov_b64 s[36:37], 0xeb20000
	v_or_b32_e32 v12, v12, v9
	v_readlane_b32 s6, v250, 7
	v_readlane_b32 s8, v250, 9
	v_readlane_b32 s9, v250, 10
	v_readlane_b32 s10, v250, 11
	v_readlane_b32 s11, v250, 12
	v_or_b32_e32 v14, v14, v9
	v_lshl_add_u64 v[16:17], s[4:5], 0, v[16:17]
	s_mov_b32 s4, s12
	v_xor_b32_e32 v5, 4, v168
	v_xor_b32_e32 v54, 8, v168
	v_xor_b32_e32 v55, 16, v168
	v_xor_b32_e32 v56, 32, v168
	v_xor_b32_e32 v57, 64, v168
	v_xor_b32_e32 v58, 0x80, v168
	v_lshl_add_u64 v[0:1], s[38:39], 0, v[0:1]
	v_and_b32_e32 v4, 32, v4
	v_lshl_add_u64 v[6:7], v[6:7], 0, s[36:37]
	s_lshl_b64 s[86:87], s[12:13], 14
	v_readlane_b32 s7, v250, 8
	s_movk_i32 s6, 0xff
	v_lshl_add_u64 v[12:13], s[8:9], 0, v[12:13]
	v_lshl_add_u64 v[14:15], s[8:9], 0, v[14:15]
	s_lshl_b64 s[8:9], s[12:13], 9
	v_writelane_b32 v250, s4, 27
	s_lshl_b64 s[10:11], s[12:13], 11
	s_mov_b64 s[84:85], 0
	v_lshlrev_b32_e32 v168, 1, v168
	v_readlane_b32 s16, v252, 15
	v_readlane_b32 s17, v252, 16
	v_readlane_b32 s18, v252, 17
	v_readlane_b32 s19, v252, 18
	v_writelane_b32 v250, s5, 28
	v_readfirstlane_b32 s44, v8
	s_cmp_lt_i32 s44, 1
	s_cbranch_scc1 .LBB0_279
	s_branch .Lp3fast

.LBB0_801:
	s_or_b64 exec, exec, s[44:45]
	v_lshlrev_b32_e32 v128, 6, v129
	v_add_u32_e32 v128, v128, v132
	v_subrev_u32_e32 v128, s59, v128
	v_add_u32_e32 v128, s50, v128
	v_lshlrev_b32_e32 v129, 3, v131
	s_lshl_b64 s[42:43], s[42:43], 2
	v_add_u32_e32 v132, 0xffffff50, v128
	v_lshl_or_b32 v129, v130, 5, v129
	s_add_u32 s42, s38, s42
	v_ashrrev_i32_e32 v133, 31, v132
	s_addc_u32 s43, s39, s43
	v_lshlrev_b32_e32 v130, 2, v129
	v_lshlrev_b64 v[140:141], 11, v[132:133]
	global_load_dwordx4 v[188:191], v130, s[42:43] offset:16
	global_load_dwordx4 v[184:187], v130, s[42:43]
	global_load_dwordx4 v[196:199], v130, s[42:43] offset:528
	global_load_dwordx4 v[192:195], v130, s[42:43] offset:512
	s_waitcnt vmcnt(0)
	v_lshlrev_b32_e32 v168, 1, v129
	v_ashrrev_i32_e32 v129, 31, v128
	v_readlane_b32 s4, v250, 32
	s_add_i32 s58, s58, s4
	s_add_i32 s50, s50, s51
	s_cmpk_gt_i32 s58, 0x7f
	v_pk_mul_f32 v[120:121], v[120:121], v[188:189]
	v_pk_mul_f32 v[124:125], v[124:125], v[184:185]
	v_pk_mul_f32 v[126:127], v[126:127], v[186:187]
	v_cvt_pk_bf16_f32 v124, v124, v125
	v_cvt_pk_bf16_f32 v125, v126, v127
	v_cvt_pk_bf16_f32 v126, v120, v121
	v_pk_mul_f32 v[120:121], v[122:123], v[190:191]
	s_nop 0
	v_cvt_pk_bf16_f32 v127, v120, v121
	v_lshl_add_u64 v[120:121], s[0:1], 0, v[140:141]
	v_lshl_add_u64 v[120:121], v[120:121], 0, s[40:41]
	v_lshl_add_u64 v[132:133], v[120:121], 0, v[168:169]
	global_store_dwordx4 v[132:133], v[124:127], off
	s_nop 0
	v_pk_mul_f32 v[112:113], v[112:113], v[196:197]
	v_pk_mul_f32 v[116:117], v[116:117], v[192:193]
	v_pk_mul_f32 v[118:119], v[118:119], v[194:195]
	v_cvt_pk_bf16_f32 v116, v116, v117
	v_cvt_pk_bf16_f32 v117, v118, v119
	v_cvt_pk_bf16_f32 v118, v112, v113
	v_pk_mul_f32 v[112:113], v[114:115], v[198:199]
	s_nop 0
	v_cvt_pk_bf16_f32 v119, v112, v113
	v_add_u32_e32 v112, 0xffffff60, v128
	global_store_dwordx4 v[132:133], v[116:119], off offset:256
	v_ashrrev_i32_e32 v113, 31, v112
	v_lshlrev_b64 v[120:121], 11, v[112:113]
	v_pk_mul_f32 v[104:105], v[104:105], v[188:189]
	v_pk_mul_f32 v[108:109], v[108:109], v[184:185]
	v_pk_mul_f32 v[110:111], v[110:111], v[186:187]
	v_cvt_pk_bf16_f32 v108, v108, v109
	v_cvt_pk_bf16_f32 v109, v110, v111
	v_cvt_pk_bf16_f32 v110, v104, v105
	v_pk_mul_f32 v[104:105], v[106:107], v[190:191]
	s_nop 0
	v_cvt_pk_bf16_f32 v111, v104, v105
	v_lshl_add_u64 v[104:105], s[0:1], 0, v[120:121]
	v_lshl_add_u64 v[104:105], v[104:105], 0, s[40:41]
	v_lshl_add_u64 v[112:113], v[104:105], 0, v[168:169]
	global_store_dwordx4 v[112:113], v[108:111], off
	s_nop 0
	v_pk_mul_f32 v[96:97], v[96:97], v[196:197]
	v_pk_mul_f32 v[100:101], v[100:101], v[192:193]
	v_pk_mul_f32 v[102:103], v[102:103], v[194:195]
	v_cvt_pk_bf16_f32 v100, v100, v101
	v_cvt_pk_bf16_f32 v101, v102, v103
	v_cvt_pk_bf16_f32 v102, v96, v97
	v_pk_mul_f32 v[96:97], v[98:99], v[198:199]
	s_nop 0
	v_cvt_pk_bf16_f32 v103, v96, v97
	v_add_u32_e32 v96, 0xffffff70, v128
	global_store_dwordx4 v[112:113], v[100:103], off offset:256
	v_ashrrev_i32_e32 v97, 31, v96
	v_lshlrev_b64 v[104:105], 11, v[96:97]
	v_pk_mul_f32 v[88:89], v[88:89], v[188:189]
	v_pk_mul_f32 v[92:93], v[92:93], v[184:185]
	v_pk_mul_f32 v[94:95], v[94:95], v[186:187]
	v_cvt_pk_bf16_f32 v92, v92, v93
	v_cvt_pk_bf16_f32 v93, v94, v95
	v_cvt_pk_bf16_f32 v94, v88, v89
	v_pk_mul_f32 v[88:89], v[90:91], v[190:191]
	s_nop 0
	v_cvt_pk_bf16_f32 v95, v88, v89
	v_lshl_add_u64 v[88:89], s[0:1], 0, v[104:105]
	v_lshl_add_u64 v[88:89], v[88:89], 0, s[40:41]
	v_lshl_add_u64 v[96:97], v[88:89], 0, v[168:169]
	global_store_dwordx4 v[96:97], v[92:95], off
	s_nop 0
	v_pk_mul_f32 v[80:81], v[80:81], v[196:197]
	v_pk_mul_f32 v[84:85], v[84:85], v[192:193]
	v_pk_mul_f32 v[86:87], v[86:87], v[194:195]
	v_cvt_pk_bf16_f32 v84, v84, v85
	v_cvt_pk_bf16_f32 v85, v86, v87
	v_cvt_pk_bf16_f32 v86, v80, v81
	v_pk_mul_f32 v[80:81], v[82:83], v[198:199]
	s_nop 0
	v_cvt_pk_bf16_f32 v87, v80, v81
	v_add_u32_e32 v80, 0xffffff80, v128
	global_store_dwordx4 v[96:97], v[84:87], off offset:256
	v_ashrrev_i32_e32 v81, 31, v80
	v_lshlrev_b64 v[88:89], 11, v[80:81]
	v_pk_mul_f32 v[72:73], v[72:73], v[188:189]
	v_pk_mul_f32 v[76:77], v[76:77], v[184:185]
	v_pk_mul_f32 v[78:79], v[78:79], v[186:187]
	v_cvt_pk_bf16_f32 v76, v76, v77
	v_cvt_pk_bf16_f32 v77, v78, v79
	v_cvt_pk_bf16_f32 v78, v72, v73
	v_pk_mul_f32 v[72:73], v[74:75], v[190:191]
	s_nop 0
	v_cvt_pk_bf16_f32 v79, v72, v73
	v_lshl_add_u64 v[72:73], s[0:1], 0, v[88:89]
	v_lshl_add_u64 v[72:73], v[72:73], 0, s[40:41]
	v_lshl_add_u64 v[80:81], v[72:73], 0, v[168:169]
	global_store_dwordx4 v[80:81], v[76:79], off
	s_nop 0
	v_pk_mul_f32 v[64:65], v[64:65], v[196:197]
	v_pk_mul_f32 v[68:69], v[68:69], v[192:193]
	v_pk_mul_f32 v[70:71], v[70:71], v[194:195]
	v_cvt_pk_bf16_f32 v68, v68, v69
	v_cvt_pk_bf16_f32 v69, v70, v71
	v_cvt_pk_bf16_f32 v70, v64, v65
	v_pk_mul_f32 v[64:65], v[66:67], v[198:199]
	s_nop 0
	v_cvt_pk_bf16_f32 v71, v64, v65
	v_subrev_u32_e32 v64, 48, v128
	global_store_dwordx4 v[80:81], v[68:71], off offset:256
	v_ashrrev_i32_e32 v65, 31, v64
	v_lshlrev_b64 v[72:73], 11, v[64:65]
	v_pk_mul_f32 v[56:57], v[56:57], v[188:189]
	v_pk_mul_f32 v[60:61], v[60:61], v[184:185]
	v_pk_mul_f32 v[62:63], v[62:63], v[186:187]
	v_cvt_pk_bf16_f32 v60, v60, v61
	v_cvt_pk_bf16_f32 v61, v62, v63
	v_cvt_pk_bf16_f32 v62, v56, v57
	v_pk_mul_f32 v[56:57], v[58:59], v[190:191]
	s_nop 0
	v_cvt_pk_bf16_f32 v63, v56, v57
	v_lshl_add_u64 v[56:57], s[0:1], 0, v[72:73]
	v_lshl_add_u64 v[56:57], v[56:57], 0, s[40:41]
	v_lshl_add_u64 v[64:65], v[56:57], 0, v[168:169]
	global_store_dwordx4 v[64:65], v[60:63], off
	s_nop 0
	v_pk_mul_f32 v[48:49], v[48:49], v[196:197]
	v_pk_mul_f32 v[52:53], v[52:53], v[192:193]
	v_pk_mul_f32 v[54:55], v[54:55], v[194:195]
	v_cvt_pk_bf16_f32 v52, v52, v53
	v_cvt_pk_bf16_f32 v53, v54, v55
	v_cvt_pk_bf16_f32 v54, v48, v49
	v_pk_mul_f32 v[48:49], v[50:51], v[198:199]
	s_nop 0
	v_cvt_pk_bf16_f32 v55, v48, v49
	v_subrev_u32_e32 v48, 32, v128
	global_store_dwordx4 v[64:65], v[52:55], off offset:256
	v_ashrrev_i32_e32 v49, 31, v48
	v_lshlrev_b64 v[56:57], 11, v[48:49]
	v_pk_mul_f32 v[40:41], v[40:41], v[188:189]
	v_pk_mul_f32 v[44:45], v[44:45], v[184:185]
	v_pk_mul_f32 v[46:47], v[46:47], v[186:187]
	v_cvt_pk_bf16_f32 v44, v44, v45
	v_cvt_pk_bf16_f32 v45, v46, v47
	v_cvt_pk_bf16_f32 v46, v40, v41
	v_pk_mul_f32 v[40:41], v[42:43], v[190:191]
	s_nop 0
	v_cvt_pk_bf16_f32 v47, v40, v41
	v_lshl_add_u64 v[40:41], s[0:1], 0, v[56:57]
	v_lshl_add_u64 v[40:41], v[40:41], 0, s[40:41]
	v_lshl_add_u64 v[48:49], v[40:41], 0, v[168:169]
	global_store_dwordx4 v[48:49], v[44:47], off
	s_nop 0
	v_pk_mul_f32 v[32:33], v[32:33], v[196:197]
	v_pk_mul_f32 v[36:37], v[36:37], v[192:193]
	v_pk_mul_f32 v[38:39], v[38:39], v[194:195]
	v_cvt_pk_bf16_f32 v36, v36, v37
	v_cvt_pk_bf16_f32 v37, v38, v39
	v_cvt_pk_bf16_f32 v38, v32, v33
	v_pk_mul_f32 v[32:33], v[34:35], v[198:199]
	s_nop 0
	v_cvt_pk_bf16_f32 v39, v32, v33
	v_add_u32_e32 v32, -16, v128
	global_store_dwordx4 v[48:49], v[36:39], off offset:256
	v_ashrrev_i32_e32 v33, 31, v32
	v_lshlrev_b64 v[40:41], 11, v[32:33]
	v_pk_mul_f32 v[24:25], v[24:25], v[188:189]
	v_pk_mul_f32 v[28:29], v[28:29], v[184:185]
	v_pk_mul_f32 v[30:31], v[30:31], v[186:187]
	v_cvt_pk_bf16_f32 v28, v28, v29
	v_cvt_pk_bf16_f32 v29, v30, v31
	v_cvt_pk_bf16_f32 v30, v24, v25
	v_pk_mul_f32 v[24:25], v[26:27], v[190:191]
	s_nop 0
	v_cvt_pk_bf16_f32 v31, v24, v25
	v_lshl_add_u64 v[24:25], s[0:1], 0, v[40:41]
	v_lshl_add_u64 v[24:25], v[24:25], 0, s[40:41]
	v_lshl_add_u64 v[32:33], v[24:25], 0, v[168:169]
	global_store_dwordx4 v[32:33], v[28:31], off
	s_nop 0
	v_pk_mul_f32 v[16:17], v[16:17], v[196:197]
	v_pk_mul_f32 v[20:21], v[20:21], v[192:193]
	v_pk_mul_f32 v[22:23], v[22:23], v[194:195]
	v_cvt_pk_bf16_f32 v20, v20, v21
	v_cvt_pk_bf16_f32 v21, v22, v23
	v_cvt_pk_bf16_f32 v22, v16, v17
	v_pk_mul_f32 v[16:17], v[18:19], v[198:199]
	v_lshlrev_b64 v[24:25], 11, v[128:129]
	v_cvt_pk_bf16_f32 v23, v16, v17
	global_store_dwordx4 v[32:33], v[20:23], off offset:256
	s_nop 0
	v_pk_mul_f32 v[8:9], v[8:9], v[188:189]
	v_pk_mul_f32 v[12:13], v[12:13], v[184:185]
	v_pk_mul_f32 v[14:15], v[14:15], v[186:187]
	v_cvt_pk_bf16_f32 v12, v12, v13
	v_cvt_pk_bf16_f32 v13, v14, v15
	v_cvt_pk_bf16_f32 v14, v8, v9
	v_pk_mul_f32 v[8:9], v[10:11], v[190:191]
	s_nop 0
	v_cvt_pk_bf16_f32 v15, v8, v9
	v_lshl_add_u64 v[8:9], s[0:1], 0, v[24:25]
	v_lshl_add_u64 v[8:9], v[8:9], 0, s[40:41]
	v_lshl_add_u64 v[16:17], v[8:9], 0, v[168:169]
	global_store_dwordx4 v[16:17], v[12:15], off
	s_nop 0
	v_pk_mul_f32 v[0:1], v[0:1], v[196:197]
	v_pk_mul_f32 v[4:5], v[4:5], v[192:193]
	v_pk_mul_f32 v[6:7], v[6:7], v[194:195]
	v_cvt_pk_bf16_f32 v4, v4, v5
	v_cvt_pk_bf16_f32 v5, v6, v7
	v_cvt_pk_bf16_f32 v6, v0, v1
	v_pk_mul_f32 v[0:1], v[2:3], v[198:199]
	s_nop 0
	v_cvt_pk_bf16_f32 v7, v0, v1
	global_store_dwordx4 v[16:17], v[4:7], off offset:256
	s_cbranch_scc1 .LBB0_806
